# v30 + prologue transposes: LDS tile double-buffered, one barrier per item instead of two
# baseline (speedup 1.0000x reference)
; #define LAS __attribute__((address_space(3)))
; __device__ __forceinline__ void transpose_item(const float* W, int K, int N, bf16_t* WT, int item, int gu, LAS float* tile,
;                                                const float* gam = nullptr, const float* bet = nullptr, float* c1p = nullptr, float* c2p = nullptr) {
;     const int tid = threadIdx.x, nblk = N / 64, kb = item / nblk, nb = item % nblk, k0 = kb * 64, n0 = nb * 64;
;     { const int r = tid >> 3, c8 = (tid & 7) * 8; const float* src = W + (size_t)(k0 + r) * N + n0 + c8;
;       const f32x4 a = *(const GASP f32x4*)src, b = *(const GASP f32x4*)(src + 4);
;       LAS float* t = tile + r * 65 + c8; t[0] = a[0]; t[1] = a[1]; t[2] = a[2]; t[3] = a[3]; t[4] = b[0]; t[5] = b[1]; t[6] = b[2]; t[7] = b[3]; }
;     __syncthreads();
;     { const int n = tid >> 3, k8 = (tid & 7) * 8; const LAS float* t = tile + k8 * 65 + n;
;       float w[8];
; #pragma unroll
;       for (int i = 0; i < 8; ++i) w[i] = t[i * 65];
;       int nn = n0 + n; if (gu) nn = (nn < FF) ? ((nn >> 7) * 256 + (nn & 127)) : (((nn - FF) >> 7) * 256 + 128 + ((nn - FF) & 127));
;       float s2 = 0.f;
;       if (gam) {
; #pragma unroll
;           for (int i = 0; i < 8; ++i) { s2 += bet[k0 + k8 + i] * w[i]; w[i] *= gam[k0 + k8 + i]; }
;       }
;       u32x4 o; o.x = pk2(w[0], w[1]); o.y = pk2(w[2], w[3]); o.z = pk2(w[4], w[5]); o.w = pk2(w[6], w[7]);
;       *(GASP u32x4*)(WT + (size_t)nn * K + k0 + k8) = o;
;       if (gam) {
;           float s1 = ((__uint_as_float(o.x << 16) + __uint_as_float(o.x & 0xffff0000u)) + (__uint_as_float(o.y << 16) + __uint_as_float(o.y & 0xffff0000u)))
;                    + ((__uint_as_float(o.z << 16) + __uint_as_float(o.z & 0xffff0000u)) + (__uint_as_float(o.w << 16) + __uint_as_float(o.w & 0xffff0000u)));
;           s1 += __shfl_xor(s1, 1); s1 += __shfl_xor(s1, 2); s1 += __shfl_xor(s1, 4);
;           s2 += __shfl_xor(s2, 1); s2 += __shfl_xor(s2, 2); s2 += __shfl_xor(s2, 4);
;           if ((tid & 7) == 0) { c1p[(size_t)kb * NC12 + nn] = s1; c2p[(size_t)kb * NC12 + nn] = s2; }
;       } }
;     __syncthreads();
; }
; __device__ __forceinline__ void phase_prep(const Params& p, LAS unsigned char* lds) {
;     ...
;     for (int it = bx; it < NIT; it += G) {
;         int r = it;
;         if (r < I_GU) { transpose_item(p.in[7], D, 2 * FF, (bf16_t*)(ws + O_WGU1), r, 1, tile); continue; } r -= I_GU;
.LBB0_21:
	s_or_b64 exec, exec, vcc
	v_ashrrev_i32_e32 v17, 31, v16
	s_waitcnt lgkmcnt(3)
	v_cvt_pk_bf16_f32 v0, v0, v1
	s_waitcnt lgkmcnt(2)
	v_cvt_pk_bf16_f32 v1, v2, v3
	s_waitcnt lgkmcnt(1)
	v_cvt_pk_bf16_f32 v2, v12, v13
	v_lshlrev_b64 v[12:13], 11, v[16:17]
	v_lshl_add_u64 v[12:13], s[88:89], 0, v[12:13]
	s_ashr_i32 s9, s8, 31
	v_lshl_add_u64 v[12:13], s[8:9], 1, v[12:13]
	v_mov_b32_e32 v11, v7
	s_waitcnt lgkmcnt(0)
	v_cvt_pk_bf16_f32 v3, v14, v15
	v_lshl_add_u64 v[12:13], v[12:13], 0, v[10:11]
	global_store_dwordx4 v[12:13], v[0:3], off
.LBB0_22:
	v_readlane_b32 s10, v252, 1
	v_readlane_b32 s11, v252, 2
	s_load_dwordx2 s[8:9], s[10:11], 0x128
	s_add_i32 s0, s0, s1
	s_add_i32 s5, s5, s33
	v_add_u32_e32 v21, s4, v21
	s_waitcnt lgkmcnt(0)
	s_add_i32 s90, s90, s8
	s_cmpk_gt_i32 s90, 0x17ff
	s_cbranch_scc1 .LBB0_87
.LBB0_23:
	v_xor_b32_e32 v18, 0x8000, v18
	v_xor_b32_e32 v19, 0x8000, v19
	v_xor_b32_e32 v22, 0x8000, v22
	s_cmpk_gt_i32 s90, 0x57f
	s_mov_b64 s[8:9], -1
	s_cbranch_scc0 .LBB0_82
	s_cmpk_gt_u32 s90, 0xaff
	s_cbranch_scc0 .LBB0_68
	s_cmpk_gt_u32 s90, 0xdbf
	s_cbranch_scc0 .LBB0_65
	s_cmpk_gt_u32 s90, 0x107f
	s_cbranch_scc0 .LBB0_62
	s_cmpk_gt_u32 s90, 0x12ff
	s_cbranch_scc0 .LBB0_52
	s_cmpk_gt_u32 s90, 0x13ff
	s_cbranch_scc0 .LBB0_49
	s_and_b32 s91, s0, 0x3c0
	s_cmpk_gt_u32 s90, 0x14ff
	s_cbranch_scc0 .LBB0_39
	s_and_b32 s10, s5, 0x3c0
	s_cmpk_gt_u32 s90, 0x15ff
	v_add_lshl_u32 v0, s10, v5, 10
	s_cbranch_scc0 .LBB0_36
	s_cmpk_gt_u32 s90, 0x16ff
	s_cbranch_scc0 .LBB0_33
	v_lshlrev_b32_e32 v6, 2, v0
	v_lshl_add_u64 v[2:3], s[48:49], 0, v[6:7]
	s_lshl_b32 s96, s91, 2
	v_lshl_add_u64 v[2:3], v[2:3], 0, s[96:97]
	v_mov_b32_e32 v9, v7
	v_lshl_add_u64 v[2:3], v[2:3], 0, v[8:9]
	global_load_dwordx4 v[12:15], v[2:3], off
	global_load_dwordx4 v[24:27], v[2:3], off offset:16
	v_readlane_b32 s8, v252, 8
	v_add_lshl_u32 v6, s91, v5, 11
	v_readlane_b32 s9, v252, 9
	s_lshl_b32 s96, s10, 1
	v_mov_b32_e32 v11, v7
	v_lshl_add_u64 v[2:3], s[8:9], 0, v[6:7]
	v_lshl_add_u64 v[2:3], v[2:3], 0, s[96:97]
	v_lshl_add_u64 v[2:3], v[2:3], 0, v[10:11]
	s_mov_b64 s[8:9], 0
	s_waitcnt vmcnt(0)
	ds_write2_b32 v18, v12, v13 offset1:1
	ds_write2_b32 v18, v14, v15 offset0:2 offset1:3
	ds_write2_b32 v18, v24, v25 offset0:4 offset1:5
	ds_write2_b32 v18, v26, v27 offset0:6 offset1:7
	s_waitcnt lgkmcnt(0)
	s_barrier
	ds_read2_b32 v[12:13], v19 offset1:65
	ds_read2_b32 v[14:15], v19 offset0:130 offset1:195
	ds_read2_b32 v[16:17], v22 offset0:4 offset1:69
	ds_read2_b32 v[24:25], v22 offset0:134 offset1:199
	s_waitcnt lgkmcnt(3)
	v_cvt_pk_bf16_f32 v12, v12, v13
	s_waitcnt lgkmcnt(2)
	v_cvt_pk_bf16_f32 v13, v14, v15
	s_waitcnt lgkmcnt(1)
	v_cvt_pk_bf16_f32 v14, v16, v17
	s_waitcnt lgkmcnt(0)
	v_cvt_pk_bf16_f32 v15, v24, v25
	global_store_dwordx4 v[2:3], v[12:15], off
.LBB0_33:
	s_andn2_b64 vcc, exec, s[8:9]
	s_cbranch_vccnz .LBB0_35
	v_lshlrev_b32_e32 v6, 2, v0
	v_lshl_add_u64 v[2:3], s[46:47], 0, v[6:7]
	s_lshl_b32 s96, s91, 2
	v_lshl_add_u64 v[2:3], v[2:3], 0, s[96:97]
	v_mov_b32_e32 v9, v7
	v_lshl_add_u64 v[2:3], v[2:3], 0, v[8:9]
	global_load_dwordx4 v[12:15], v[2:3], off
	global_load_dwordx4 v[24:27], v[2:3], off offset:16
	v_readlane_b32 s8, v252, 10
	v_add_lshl_u32 v6, s91, v5, 11
	v_readlane_b32 s9, v252, 11
	s_lshl_b32 s96, s10, 1
	v_mov_b32_e32 v11, v7
	v_lshl_add_u64 v[2:3], s[8:9], 0, v[6:7]
	v_lshl_add_u64 v[2:3], v[2:3], 0, s[96:97]
	v_lshl_add_u64 v[2:3], v[2:3], 0, v[10:11]
	s_waitcnt vmcnt(0)
	ds_write2_b32 v18, v12, v13 offset1:1
	ds_write2_b32 v18, v14, v15 offset0:2 offset1:3
	ds_write2_b32 v18, v24, v25 offset0:4 offset1:5
	ds_write2_b32 v18, v26, v27 offset0:6 offset1:7
	s_waitcnt lgkmcnt(0)
	s_barrier
	ds_read2_b32 v[12:13], v19 offset1:65
	ds_read2_b32 v[14:15], v19 offset0:130 offset1:195
	ds_read2_b32 v[16:17], v22 offset0:4 offset1:69
	ds_read2_b32 v[24:25], v22 offset0:134 offset1:199
	s_waitcnt lgkmcnt(3)
	v_cvt_pk_bf16_f32 v12, v12, v13
	s_waitcnt lgkmcnt(2)
	v_cvt_pk_bf16_f32 v13, v14, v15
	s_waitcnt lgkmcnt(1)
	v_cvt_pk_bf16_f32 v14, v16, v17
	s_waitcnt lgkmcnt(0)
	v_cvt_pk_bf16_f32 v15, v24, v25
	global_store_dwordx4 v[2:3], v[12:15], off
.LBB0_35:
	s_mov_b64 s[8:9], 0
.LBB0_36:
	s_andn2_b64 vcc, exec, s[8:9]
	s_cbranch_vccnz .LBB0_38
	v_lshlrev_b32_e32 v6, 2, v0
	v_lshl_add_u64 v[0:1], s[44:45], 0, v[6:7]
	s_lshl_b32 s96, s91, 2
	v_lshl_add_u64 v[0:1], v[0:1], 0, s[96:97]
	v_mov_b32_e32 v9, v7
	v_lshl_add_u64 v[12:13], v[0:1], 0, v[8:9]
	global_load_dwordx4 v[0:3], v[12:13], off
	s_nop 0
	global_load_dwordx4 v[12:15], v[12:13], off offset:16
	v_add_lshl_u32 v6, s91, v5, 11
	v_lshl_add_u64 v[16:17], s[62:63], 0, v[6:7]
	s_lshl_b32 s96, s10, 1
	v_mov_b32_e32 v11, v7
	v_lshl_add_u64 v[16:17], v[16:17], 0, s[96:97]
	v_lshl_add_u64 v[16:17], v[16:17], 0, v[10:11]
	s_waitcnt vmcnt(0)
	ds_write2_b32 v18, v0, v1 offset1:1
	ds_write2_b32 v18, v2, v3 offset0:2 offset1:3
	ds_write2_b32 v18, v12, v13 offset0:4 offset1:5
	ds_write2_b32 v18, v14, v15 offset0:6 offset1:7
	s_waitcnt lgkmcnt(0)
	s_barrier
	ds_read2_b32 v[0:1], v19 offset1:65
	ds_read2_b32 v[2:3], v19 offset0:130 offset1:195
	ds_read2_b32 v[12:13], v22 offset0:4 offset1:69
	ds_read2_b32 v[14:15], v22 offset0:134 offset1:199
	s_waitcnt lgkmcnt(3)
	v_cvt_pk_bf16_f32 v0, v0, v1
	s_waitcnt lgkmcnt(2)
	v_cvt_pk_bf16_f32 v1, v2, v3
	s_waitcnt lgkmcnt(1)
	v_cvt_pk_bf16_f32 v2, v12, v13
	s_waitcnt lgkmcnt(0)
	v_cvt_pk_bf16_f32 v3, v14, v15
	global_store_dwordx4 v[16:17], v[0:3], off
.LBB0_38:
	s_mov_b64 s[8:9], 0

; #define LAS __attribute__((address_space(3)))
; #define GASP __attribute__((address_space(1)))
; __device__ __forceinline__ void transpose_item(const float* W, int K, int N, bf16_t* WT, int item, int gu, LAS float* tile,
;                                                const float* gam = nullptr, const float* bet = nullptr, float* c1p = nullptr, float* c2p = nullptr) {
;     const int tid = threadIdx.x, nblk = N / 64, kb = item / nblk, nb = item % nblk, k0 = kb * 64, n0 = nb * 64;
;     { const int r = tid >> 3, c8 = (tid & 7) * 8; const float* src = W + (size_t)(k0 + r) * N + n0 + c8;
;       const f32x4 a = *(const GASP f32x4*)src, b = *(const GASP f32x4*)(src + 4);
;       LAS float* t = tile + r * 65 + c8; t[0] = a[0]; t[1] = a[1]; t[2] = a[2]; t[3] = a[3]; t[4] = b[0]; t[5] = b[1]; t[6] = b[2]; t[7] = b[3]; }
;     __syncthreads();
;     { const int n = tid >> 3, k8 = (tid & 7) * 8; const LAS float* t = tile + k8 * 65 + n;
;       float w[8];
; #pragma unroll
;       for (int i = 0; i < 8; ++i) w[i] = t[i * 65];
;       int nn = n0 + n; if (gu) nn = (nn < FF) ? ((nn >> 7) * 256 + (nn & 127)) : (((nn - FF) >> 7) * 256 + 128 + ((nn - FF) & 127));
;       float s2 = 0.f;
;       if (gam) {
; #pragma unroll
;           for (int i = 0; i < 8; ++i) { s2 += bet[k0 + k8 + i] * w[i]; w[i] *= gam[k0 + k8 + i]; }
;       }
;       u32x4 o; o.x = pk2(w[0], w[1]); o.y = pk2(w[2], w[3]); o.z = pk2(w[4], w[5]); o.w = pk2(w[6], w[7]);
;       *(GASP u32x4*)(WT + (size_t)nn * K + k0 + k8) = o;
;       if (gam) {
;           float s1 = ((__uint_as_float(o.x << 16) + __uint_as_float(o.x & 0xffff0000u)) + (__uint_as_float(o.y << 16) + __uint_as_float(o.y & 0xffff0000u)))
;                    + ((__uint_as_float(o.z << 16) + __uint_as_float(o.z & 0xffff0000u)) + (__uint_as_float(o.w << 16) + __uint_as_float(o.w & 0xffff0000u)));
;           s1 += __shfl_xor(s1, 1); s1 += __shfl_xor(s1, 2); s1 += __shfl_xor(s1, 4);
;           s2 += __shfl_xor(s2, 1); s2 += __shfl_xor(s2, 2); s2 += __shfl_xor(s2, 4);
;           if ((tid & 7) == 0) { c1p[(size_t)kb * NC12 + nn] = s1; c2p[(size_t)kb * NC12 + nn] = s2; }
;       } }
;     __syncthreads();
; }
; __device__ __forceinline__ void phase_prep(const Params& p, LAS unsigned char* lds) {
;     ...
;         if (r < I_SQ) { transpose_item(p.in[21], D, D, (bf16_t*)(ws + O_WOUT), r, 0, tile); continue; } r -= I_SQ;
.LBB0_47:
	s_waitcnt lgkmcnt(0)
.LBB0_48:
	s_mov_b64 s[8:9], 0
.LBB0_49:
	s_andn2_b64 vcc, exec, s[8:9]
	s_cbranch_vccnz .LBB0_51
	s_and_b32 s8, s5, 0x3c0
	s_and_b32 s9, s0, 0x3c0
	v_add_lshl_u32 v6, s8, v5, 12
	v_lshl_add_u64 v[0:1], s[36:37], 0, v[6:7]
	s_lshl_b32 s96, s9, 2
	v_lshl_add_u64 v[0:1], v[0:1], 0, s[96:97]
	v_mov_b32_e32 v9, v7
	v_lshl_add_u64 v[12:13], v[0:1], 0, v[8:9]
	global_load_dwordx4 v[0:3], v[12:13], off
	s_nop 0
	global_load_dwordx4 v[12:15], v[12:13], off offset:16
	v_add_lshl_u32 v6, s9, v5, 11
	v_lshl_add_u64 v[16:17], s[70:71], 0, v[6:7]
	s_lshl_b32 s96, s8, 1
	v_mov_b32_e32 v11, v7
	v_lshl_add_u64 v[16:17], v[16:17], 0, s[96:97]
	v_lshl_add_u64 v[16:17], v[16:17], 0, v[10:11]
	s_waitcnt vmcnt(0)
	ds_write2_b32 v18, v0, v1 offset1:1
	ds_write2_b32 v18, v2, v3 offset0:2 offset1:3
	ds_write2_b32 v18, v12, v13 offset0:4 offset1:5
	ds_write2_b32 v18, v14, v15 offset0:6 offset1:7
	s_waitcnt lgkmcnt(0)
	s_barrier
	ds_read2_b32 v[0:1], v19 offset1:65
	ds_read2_b32 v[2:3], v19 offset0:130 offset1:195
	ds_read2_b32 v[12:13], v22 offset0:4 offset1:69
	ds_read2_b32 v[14:15], v22 offset0:134 offset1:199
	s_waitcnt lgkmcnt(3)
	v_cvt_pk_bf16_f32 v0, v0, v1
	s_waitcnt lgkmcnt(2)
	v_cvt_pk_bf16_f32 v1, v2, v3
	s_waitcnt lgkmcnt(1)
	v_cvt_pk_bf16_f32 v2, v12, v13
	s_waitcnt lgkmcnt(0)
	v_cvt_pk_bf16_f32 v3, v14, v15
	global_store_dwordx4 v[16:17], v[0:3], off
.LBB0_51:
	s_mov_b64 s[8:9], 0

; __device__ __forceinline__ void transpose_item(const float* W, int K, int N, bf16_t* WT, int item, int gu, LAS float* tile,
;                                                const float* gam = nullptr, const float* bet = nullptr, float* c1p = nullptr, float* c2p = nullptr) {
;     const int tid = threadIdx.x, nblk = N / 64, kb = item / nblk, nb = item % nblk, k0 = kb * 64, n0 = nb * 64;
;     { const int r = tid >> 3, c8 = (tid & 7) * 8; const float* src = W + (size_t)(k0 + r) * N + n0 + c8;
;       const f32x4 a = *(const GASP f32x4*)src, b = *(const GASP f32x4*)(src + 4);
;       LAS float* t = tile + r * 65 + c8; t[0] = a[0]; t[1] = a[1]; t[2] = a[2]; t[3] = a[3]; t[4] = b[0]; t[5] = b[1]; t[6] = b[2]; t[7] = b[3]; }
;     __syncthreads();
;     { const int n = tid >> 3, k8 = (tid & 7) * 8; const LAS float* t = tile + k8 * 65 + n;
;       float w[8];
; #pragma unroll
;       for (int i = 0; i < 8; ++i) w[i] = t[i * 65];
;       int nn = n0 + n; if (gu) nn = (nn < FF) ? ((nn >> 7) * 256 + (nn & 127)) : (((nn - FF) >> 7) * 256 + 128 + ((nn - FF) & 127));
;       float s2 = 0.f;
;       if (gam) {
; #pragma unroll
;           for (int i = 0; i < 8; ++i) { s2 += bet[k0 + k8 + i] * w[i]; w[i] *= gam[k0 + k8 + i]; }
;       }
;       u32x4 o; o.x = pk2(w[0], w[1]); o.y = pk2(w[2], w[3]); o.z = pk2(w[4], w[5]); o.w = pk2(w[6], w[7]);
;       *(GASP u32x4*)(WT + (size_t)nn * K + k0 + k8) = o;
;       if (gam) {
;           float s1 = ((__uint_as_float(o.x << 16) + __uint_as_float(o.x & 0xffff0000u)) + (__uint_as_float(o.y << 16) + __uint_as_float(o.y & 0xffff0000u)))
;                    + ((__uint_as_float(o.z << 16) + __uint_as_float(o.z & 0xffff0000u)) + (__uint_as_float(o.w << 16) + __uint_as_float(o.w & 0xffff0000u)));
;           s1 += __shfl_xor(s1, 1); s1 += __shfl_xor(s1, 2); s1 += __shfl_xor(s1, 4);
;           s2 += __shfl_xor(s2, 1); s2 += __shfl_xor(s2, 2); s2 += __shfl_xor(s2, 4);
;           if ((tid & 7) == 0) { c1p[(size_t)kb * NC12 + nn] = s1; c2p[(size_t)kb * NC12 + nn] = s2; }
;       } }
;     __syncthreads();
; }
; __device__ __forceinline__ void phase_prep(const Params& p, LAS unsigned char* lds) {
;     ...
;         if (r < I_DN) { transpose_item(p.in[8], FF, D, (bf16_t*)(ws + O_WDN1), r, 0, tile); continue; } r -= I_DN;
;         if (r < I_DN) { transpose_item(p.in[31], FF, D, (bf16_t*)(ws + O_WDN2), r, 0, tile); continue; } r -= I_DN;
.LBB0_60:
	s_waitcnt lgkmcnt(0)
.LBB0_61:
	s_mov_b64 s[8:9], 0
.LBB0_62:
	s_andn2_b64 vcc, exec, s[8:9]
	s_cbranch_vccnz .LBB0_64
	s_add_i32 s8, s5, 0x3c900
	s_and_b32 s10, s8, 0x3ffc0
	v_readlane_b32 s8, v252, 1
	v_readlane_b32 s9, v252, 2
	s_load_dwordx2 s[8:9], s[8:9], 0xf8
	s_and_b32 s11, s0, 0x3c0
	v_add_lshl_u32 v6, s10, v5, 12
	s_lshl_b32 s96, s11, 2
	v_mov_b32_e32 v9, v7
	s_waitcnt lgkmcnt(0)
	v_lshl_add_u64 v[0:1], s[8:9], 0, v[6:7]
	v_lshl_add_u64 v[0:1], v[0:1], 0, s[96:97]
	v_lshl_add_u64 v[12:13], v[0:1], 0, v[8:9]
	global_load_dwordx4 v[0:3], v[12:13], off
	s_nop 0
	global_load_dwordx4 v[12:15], v[12:13], off offset:16
	v_add_u32_e32 v6, s11, v5
	v_mul_u32_u24_e32 v6, 0xb00, v6
	v_lshlrev_b32_e32 v6, 1, v6
	v_lshl_add_u64 v[16:17], s[78:79], 0, v[6:7]
	s_lshl_b32 s96, s10, 1
	v_mov_b32_e32 v11, v7
	v_lshl_add_u64 v[16:17], v[16:17], 0, s[96:97]
	v_lshl_add_u64 v[16:17], v[16:17], 0, v[10:11]
	s_waitcnt vmcnt(0)
	ds_write2_b32 v18, v0, v1 offset1:1
	ds_write2_b32 v18, v2, v3 offset0:2 offset1:3
	ds_write2_b32 v18, v12, v13 offset0:4 offset1:5
	ds_write2_b32 v18, v14, v15 offset0:6 offset1:7
	s_waitcnt lgkmcnt(0)
	s_barrier
	ds_read2_b32 v[0:1], v19 offset1:65
	ds_read2_b32 v[2:3], v19 offset0:130 offset1:195
	ds_read2_b32 v[12:13], v22 offset0:4 offset1:69
	ds_read2_b32 v[14:15], v22 offset0:134 offset1:199
	s_waitcnt lgkmcnt(3)
	v_cvt_pk_bf16_f32 v0, v0, v1
	s_waitcnt lgkmcnt(2)
	v_cvt_pk_bf16_f32 v1, v2, v3
	s_waitcnt lgkmcnt(1)
	v_cvt_pk_bf16_f32 v2, v12, v13
	s_waitcnt lgkmcnt(0)
	v_cvt_pk_bf16_f32 v3, v14, v15
	global_store_dwordx4 v[16:17], v[0:3], off
.LBB0_64:
	s_mov_b64 s[8:9], 0
.LBB0_65:
	s_andn2_b64 vcc, exec, s[8:9]
	s_cbranch_vccnz .LBB0_67
	s_add_i32 s8, s5, 0x3d400
	s_and_b32 s8, s8, 0x3ffc0
	s_and_b32 s9, s0, 0x3c0
	v_add_lshl_u32 v6, s8, v5, 12
	v_lshl_add_u64 v[0:1], s[20:21], 0, v[6:7]
	s_lshl_b32 s96, s9, 2
	v_lshl_add_u64 v[0:1], v[0:1], 0, s[96:97]
	v_mov_b32_e32 v9, v7
	v_lshl_add_u64 v[12:13], v[0:1], 0, v[8:9]
	global_load_dwordx4 v[0:3], v[12:13], off
	s_nop 0
	global_load_dwordx4 v[12:15], v[12:13], off offset:16
	v_add_u32_e32 v6, s9, v5
	v_mul_u32_u24_e32 v6, 0xb00, v6
	v_lshlrev_b32_e32 v6, 1, v6
	v_lshl_add_u64 v[16:17], s[80:81], 0, v[6:7]
	s_lshl_b32 s96, s8, 1
	v_mov_b32_e32 v11, v7
	v_lshl_add_u64 v[16:17], v[16:17], 0, s[96:97]
	v_lshl_add_u64 v[16:17], v[16:17], 0, v[10:11]
	s_waitcnt vmcnt(0)
	ds_write2_b32 v18, v0, v1 offset1:1
	ds_write2_b32 v18, v2, v3 offset0:2 offset1:3
	ds_write2_b32 v18, v12, v13 offset0:4 offset1:5
	ds_write2_b32 v18, v14, v15 offset0:6 offset1:7
	s_waitcnt lgkmcnt(0)
	s_barrier
	ds_read2_b32 v[0:1], v19 offset1:65
	ds_read2_b32 v[2:3], v19 offset0:130 offset1:195
	ds_read2_b32 v[12:13], v22 offset0:4 offset1:69
	ds_read2_b32 v[14:15], v22 offset0:134 offset1:199
	s_waitcnt lgkmcnt(3)
	v_cvt_pk_bf16_f32 v0, v0, v1
	s_waitcnt lgkmcnt(2)
	v_cvt_pk_bf16_f32 v1, v2, v3
	s_waitcnt lgkmcnt(1)
	v_cvt_pk_bf16_f32 v2, v12, v13
	s_waitcnt lgkmcnt(0)
	v_cvt_pk_bf16_f32 v3, v14, v15
	global_store_dwordx4 v[16:17], v[0:3], off
.LBB0_67:
	s_mov_b64 s[8:9], 0

; __device__ __forceinline__ void transpose_item(const float* W, int K, int N, bf16_t* WT, int item, int gu, LAS float* tile,
;                                                const float* gam = nullptr, const float* bet = nullptr, float* c1p = nullptr, float* c2p = nullptr) {
;     ...
;       if (gam) {
;           float s1 = ((__uint_as_float(o.x << 16) + __uint_as_float(o.x & 0xffff0000u)) + (__uint_as_float(o.y << 16) + __uint_as_float(o.y & 0xffff0000u)))
;                    + ((__uint_as_float(o.z << 16) + __uint_as_float(o.z & 0xffff0000u)) + (__uint_as_float(o.w << 16) + __uint_as_float(o.w & 0xffff0000u)));
;           s1 += __shfl_xor(s1, 1); s1 += __shfl_xor(s1, 2); s1 += __shfl_xor(s1, 4);
;           s2 += __shfl_xor(s2, 1); s2 += __shfl_xor(s2, 2); s2 += __shfl_xor(s2, 4);
;           if ((tid & 7) == 0) { c1p[(size_t)kb * NC12 + nn] = s1; c2p[(size_t)kb * NC12 + nn] = s2; }
;       } }
;     __syncthreads();
.LBB0_80:
	s_waitcnt lgkmcnt(0)
.LBB0_81:
	s_mov_b64 s[8:9], 0
